# attention all-done DPP reduction replaced by scalar compare; hgrn ssq reduction via DPP butterfly + one b128 store (on top of VT swizzle)
# speedup vs baseline: 1.0100x; 1.0015x over previous
; __device__ __forceinline__ void item_attn(const Params& p, int l, int aidx) {
;     ...
;         }
;       }
;       wave_done = __all(((carry[0] < 1e-36f) || !rowv[0]) && ((carry[1] < 1e-36f) || !rowv[1]));
;     }
;     if (__syncthreads_and(wave_done ? 1 : 0)) all_done = true;
.LBB0_694:
	s_cmp_lg_u64 s[0:1], 0
	s_cselect_b32 s22, 1, 0
	v_readlane_b32 s2, v248, 32
	v_readlane_b32 s3, v248, 33
	s_andn2_b64 vcc, exec, s[2:3]
	s_nop 0
	v_cndmask_b32_e64 v64, 0, 1, s[2:3]
	v_cmp_ne_u32_e64 s[20:21], 1, v64
	v_mov_b32_e32 v64, s22
	s_cbranch_vccnz .LBB0_701
	v_or_b32_e32 v64, v215, v193
	v_cmp_eq_u32_e32 vcc, 0, v64
	s_and_saveexec_b64 s[2:3], vcc
	v_mov_b32_e32 v64, s22
	ds_write_b32 v191, v64
	s_or_b64 exec, exec, s[2:3]
	v_cmp_eq_u32_e32 vcc, 0, v215
	s_and_b64 s[2:3], s[94:95], vcc
	s_waitcnt lgkmcnt(0)
	s_barrier
	s_and_saveexec_b64 s[4:5], s[2:3]
	s_cbranch_execz .LBB0_700
	v_mbcnt_lo_u32_b32 v64, exec_lo, 0
	v_mbcnt_hi_u32_b32 v64, exec_hi, v64
	v_cmp_eq_u32_e32 vcc, 0, v64
	s_and_b64 exec, exec, vcc
	v_mov_b32_e32 v64, s22
	ds_and_b32 v191, v64

; __device__ __forceinline__ void item_attn(const Params& p, int l, int aidx) {
;     ...
;         }
;       }
;       wave_done = __all(((carry[0] < 1e-36f) || !rowv[0]) && ((carry[1] < 1e-36f) || !rowv[1]));
;     }
;     if (__syncthreads_and(wave_done ? 1 : 0)) all_done = true;
.LBB0_767:
	s_cmp_lg_u64 s[0:1], 0
	s_cselect_b32 s22, 1, 0
	s_and_b64 vcc, exec, s[20:21]
	v_mov_b32_e32 v64, s22
	s_cbranch_vccnz .LBB0_627
	v_or_b32_e32 v64, v215, v193
	v_cmp_eq_u32_e32 vcc, 0, v64
	s_and_saveexec_b64 s[2:3], vcc
	v_mov_b32_e32 v64, s22
	ds_write_b32 v191, v64
	s_or_b64 exec, exec, s[2:3]
	v_cmp_eq_u32_e32 vcc, 0, v215
	s_and_b64 s[2:3], s[94:95], vcc
	s_waitcnt lgkmcnt(0)
	s_barrier
	s_and_saveexec_b64 s[4:5], s[2:3]
	s_cbranch_execz .LBB0_626
	v_mbcnt_lo_u32_b32 v64, exec_lo, 0
	v_mbcnt_hi_u32_b32 v64, exec_hi, v64
	v_cmp_eq_u32_e32 vcc, 0, v64
	s_and_b64 exec, exec, vcc
	s_cbranch_execz .LBB0_626
	v_mov_b32_e32 v64, s22
	ds_and_b32 v191, v64
	s_branch .LBB0_626

; __device__ __forceinline__ void item_hgrn(const Params& p, int l, int sidx) {
;     ...
; #pragma unroll
;         for (int j = 0; j < 4; ++j) {
;           int trow = tt * 16 + fq * 4 + j, scol = st * 16 + fr;
;           float v = (scol <= trow) ? pa[j] : 0.f;
;           Ps[trow * 72 + scol] = f2bf(v);
;         }
;       }
;     }
;     __syncthreads();
;     f32x4 oacc[4];
;     const int tt = wid & 3, dvh = wid >> 2;
;     {
; #pragma unroll
;       for (int n = 0; n < 4; ++n) oacc[n] = f32x4{0.f, 0.f, 0.f, 0.f};
; #pragma unroll
;       for (int ks = 0; ks < 2; ++ks) {
;         bf16x8 a = *reinterpret_cast<const bf16x8*>(Ps + (tt * 16 + fr) * 72 + ks * 32 + fq * 8);
; #pragma unroll
;         for (int n = 0; n < 4; ++n) {
;           bf16x8 bb = *reinterpret_cast<const bf16x8*>(VTs + (dvh * 64 + n * 16 + fr) * 72 + ks * 32 + fq * 8);
;           oacc[n] = __builtin_amdgcn_mfma_f32_16x16x32_bf16(a, bb, oacc[n], 0, 0, 0);
;         }
;       }
; #pragma unroll
;       for (int ks = 0; ks < 4; ++ks) {
;         bf16x8 a = *reinterpret_cast<const bf16x8*>(Qs + (tt * 16 + fr) * 136 + ks * 32 + fq * 8);
; #pragma unroll
;         for (int n = 0; n < 4; ++n) {
;           bf16x8 bb = *reinterpret_cast<const bf16x8*>(SpT + (dvh * 64 + n * 16 + fr) * 136 + ks * 32 + fq * 8);
;           oacc[n] = __builtin_amdgcn_mfma_f32_16x16x32_bf16(a, bb, oacc[n], 0, 0, 0);
;         }
;       }
.LBB0_816:
	s_nop 7
	v_cndmask_b32_e64 v40, v40, 0, s[20:21]
	v_bfe_u32 v44, v40, 16, 1
	v_add3_u32 v40, v40, v44, s80
	ds_write_b16_d16_hi v149, v40
	v_cndmask_b32_e64 v40, v41, 0, s[22:23]
	v_bfe_u32 v41, v40, 16, 1
	v_add3_u32 v40, v40, v41, s80
	ds_write_b16_d16_hi v150, v40
	v_cndmask_b32_e64 v40, v42, 0, s[24:25]
	v_bfe_u32 v41, v40, 16, 1
	v_add3_u32 v40, v40, v41, s80
	ds_write_b16_d16_hi v151, v40
	v_cndmask_b32_e64 v40, v43, 0, s[26:27]
	v_bfe_u32 v41, v40, 16, 1
	v_add3_u32 v40, v40, v41, s80
	ds_write_b16_d16_hi v152, v40
	s_waitcnt lgkmcnt(0)
	s_barrier
	ds_read_b128 v[40:43], v83
	ds_read_b128 v[44:47], v166 offset:53248
	ds_read_b128 v[48:51], v239 offset:55552
	ds_read_b128 v[52:55], v166 offset:57920
	ds_read_b128 v[56:59], v239 offset:60224
	s_waitcnt lgkmcnt(3)
	v_mfma_f32_16x16x32_bf16 v[44:47], v[40:43], v[44:47], 0
	v_xor_b32_e32 v207, 8, v215
	s_waitcnt lgkmcnt(2)
	v_mfma_f32_16x16x32_bf16 v[48:51], v[40:43], v[48:51], 0
	s_waitcnt lgkmcnt(1)
	v_mfma_f32_16x16x32_bf16 v[52:55], v[40:43], v[52:55], 0
	s_waitcnt lgkmcnt(0)
	v_mfma_f32_16x16x32_bf16 v[40:43], v[40:43], v[56:59], 0
	ds_read_b128 v[56:59], v83 offset:64
	ds_read_b128 v[218:221], v166 offset:53312
	s_waitcnt lgkmcnt(0)
	v_mfma_f32_16x16x32_bf16 v[44:47], v[56:59], v[218:221], v[44:47]
	ds_read_b128 v[218:221], v239 offset:55616
	s_waitcnt lgkmcnt(0)
	v_mfma_f32_16x16x32_bf16 v[48:51], v[56:59], v[218:221], v[48:51]
	ds_read_b128 v[218:221], v166 offset:57856
	s_waitcnt lgkmcnt(0)
	v_mfma_f32_16x16x32_bf16 v[52:55], v[56:59], v[218:221], v[52:55]
	ds_read_b128 v[218:221], v239 offset:60160
	s_waitcnt lgkmcnt(0)
	v_mfma_f32_16x16x32_bf16 v[40:43], v[56:59], v[218:221], v[40:43]
	ds_read_b128 v[56:59], v101
	ds_read_b128 v[218:221], v167
	s_waitcnt lgkmcnt(0)
	v_mfma_f32_16x16x32_bf16 v[44:47], v[56:59], v[218:221], v[44:47]
	ds_read_b128 v[218:221], v167 offset:4352
	s_waitcnt lgkmcnt(0)
	v_mfma_f32_16x16x32_bf16 v[48:51], v[56:59], v[218:221], v[48:51]
	ds_read_b128 v[218:221], v167 offset:8704
	s_waitcnt lgkmcnt(0)
	v_mfma_f32_16x16x32_bf16 v[52:55], v[56:59], v[218:221], v[52:55]
	ds_read_b128 v[218:221], v167 offset:13056
	s_waitcnt lgkmcnt(0)
	v_mfma_f32_16x16x32_bf16 v[40:43], v[56:59], v[218:221], v[40:43]
	ds_read_b128 v[56:59], v101 offset:64
	ds_read_b128 v[218:221], v167 offset:64
	s_waitcnt lgkmcnt(0)
	v_mfma_f32_16x16x32_bf16 v[44:47], v[56:59], v[218:221], v[44:47]
	ds_read_b128 v[218:221], v167 offset:4416
	s_waitcnt lgkmcnt(0)
	v_mfma_f32_16x16x32_bf16 v[48:51], v[56:59], v[218:221], v[48:51]
	ds_read_b128 v[218:221], v167 offset:8768
	s_waitcnt lgkmcnt(0)
	v_mfma_f32_16x16x32_bf16 v[52:55], v[56:59], v[218:221], v[52:55]
	ds_read_b128 v[218:221], v167 offset:13120
	s_waitcnt lgkmcnt(0)
	v_mfma_f32_16x16x32_bf16 v[40:43], v[56:59], v[218:221], v[40:43]
	ds_read_b128 v[56:59], v101 offset:128
	ds_read_b128 v[218:221], v167 offset:128
	s_waitcnt lgkmcnt(0)
	v_mfma_f32_16x16x32_bf16 v[44:47], v[56:59], v[218:221], v[44:47]
	ds_read_b128 v[218:221], v167 offset:4480
	s_waitcnt lgkmcnt(0)
	v_mfma_f32_16x16x32_bf16 v[48:51], v[56:59], v[218:221], v[48:51]
	ds_read_b128 v[218:221], v167 offset:8832
	s_waitcnt lgkmcnt(0)
	v_mfma_f32_16x16x32_bf16 v[52:55], v[56:59], v[218:221], v[52:55]
	ds_read_b128 v[218:221], v167 offset:13184
	s_waitcnt lgkmcnt(0)
	v_mfma_f32_16x16x32_bf16 v[56:59], v[56:59], v[218:221], v[40:43]
	ds_read_b128 v[218:221], v101 offset:192
	s_nop 1
	ds_read_b128 v[40:43], v167 offset:192
	s_waitcnt lgkmcnt(0)
	v_mfma_f32_16x16x32_bf16 v[40:43], v[218:221], v[40:43], v[44:47]
	s_nop 2
	ds_read_b128 v[44:47], v167 offset:4544
	s_waitcnt lgkmcnt(0)
	v_mfma_f32_16x16x32_bf16 v[44:47], v[218:221], v[44:47], v[48:51]
	s_nop 2
	ds_read_b128 v[48:51], v167 offset:8896
	s_waitcnt lgkmcnt(0)
	v_mfma_f32_16x16x32_bf16 v[48:51], v[218:221], v[48:51], v[52:55]
	s_nop 2
	ds_read_b128 v[52:55], v167 offset:13248
	s_waitcnt lgkmcnt(0)
; __device__ __forceinline__ void item_hgrn(const Params& p, int l, int sidx) {
;     ...
; #pragma unroll
;       for (int j = 0; j < 4; ++j) {
;         float ss = 0.f;
; #pragma unroll
;         for (int n = 0; n < 4; ++n) ss += oacc[n][j] * oacc[n][j];
;         ss += __shfl_xor(ss, 1); ss += __shfl_xor(ss, 2); ss += __shfl_xor(ss, 4); ss += __shfl_xor(ss, 8);
;         if (fr == 0) ssq[dvh * 64 + tt * 16 + fq * 4 + j] = ss;
;       }
;     }
;     {
; #pragma unroll
;       for (int ks = 0; ks < 2; ++ks) {
;         bf16x8 a = *reinterpret_cast<const bf16x8*>(KTs + (16 * wid + fr) * 72 + ks * 32 + fq * 8);
; #pragma unroll
;         for (int n = 0; n < 8; ++n) {
;           bf16x8 bb = *reinterpret_cast<const bf16x8*>(VTs + (n * 16 + fr) * 72 + ks * 32 + fq * 8);
;           S[n] = __builtin_amdgcn_mfma_f32_16x16x32_bf16(a, bb, S[n], 0, 0, 0);
;         }
;       }
	v_mfma_f32_16x16x32_bf16 v[52:55], v[218:221], v[52:55], v[56:59]
	s_nop 2
	v_mul_f32_e32 v56, v44, v44
	v_mul_f32_e32 v57, v45, v45
	v_mul_f32_e32 v58, v46, v46
	v_mul_f32_e32 v59, v47, v47
	v_fmac_f32_e32 v56, v40, v40
	v_fmac_f32_e32 v57, v41, v41
	v_fmac_f32_e32 v58, v42, v42
	v_fmac_f32_e32 v59, v43, v43
	v_fmac_f32_e32 v56, v48, v48
	v_fmac_f32_e32 v57, v49, v49
	v_fmac_f32_e32 v58, v50, v50
	v_fmac_f32_e32 v59, v51, v51
	v_fmac_f32_e32 v56, v52, v52
	v_fmac_f32_e32 v57, v53, v53
	v_fmac_f32_e32 v58, v54, v54
	v_fmac_f32_e32 v59, v55, v55
	v_add_f32_dpp v56, v56, v56 quad_perm:[1,0,3,2] row_mask:0xf bank_mask:0xf
	v_add_f32_dpp v57, v57, v57 quad_perm:[1,0,3,2] row_mask:0xf bank_mask:0xf
	v_add_f32_dpp v58, v58, v58 quad_perm:[1,0,3,2] row_mask:0xf bank_mask:0xf
	v_add_f32_dpp v59, v59, v59 quad_perm:[1,0,3,2] row_mask:0xf bank_mask:0xf
	v_add_f32_dpp v56, v56, v56 quad_perm:[2,3,0,1] row_mask:0xf bank_mask:0xf
	v_add_f32_dpp v57, v57, v57 quad_perm:[2,3,0,1] row_mask:0xf bank_mask:0xf
	v_add_f32_dpp v58, v58, v58 quad_perm:[2,3,0,1] row_mask:0xf bank_mask:0xf
	v_add_f32_dpp v59, v59, v59 quad_perm:[2,3,0,1] row_mask:0xf bank_mask:0xf
	v_add_f32_dpp v56, v56, v56 row_half_mirror row_mask:0xf bank_mask:0xf
	v_add_f32_dpp v57, v57, v57 row_half_mirror row_mask:0xf bank_mask:0xf
	v_add_f32_dpp v58, v58, v58 row_half_mirror row_mask:0xf bank_mask:0xf
	v_add_f32_dpp v59, v59, v59 row_half_mirror row_mask:0xf bank_mask:0xf
	v_add_f32_dpp v56, v56, v56 row_mirror row_mask:0xf bank_mask:0xf
	v_add_f32_dpp v57, v57, v57 row_mirror row_mask:0xf bank_mask:0xf
	v_add_f32_dpp v58, v58, v58 row_mirror row_mask:0xf bank_mask:0xf
	v_add_f32_dpp v59, v59, v59 row_mirror row_mask:0xf bank_mask:0xf
	v_add_u32_e32 v207, s87, v96
	s_and_saveexec_b64 s[2:3], s[10:11]
	ds_write_b128 v207, v[56:59]
	s_or_b64 exec, exec, s[2:3]
	s_waitcnt lgkmcnt(0)
	ds_read_b128 v[56:59], v84 offset:34816
	ds_read_b128 v[218:221], v168 offset:53248
	v_cmp_gt_u32_e32 vcc, s86, v206
	s_waitcnt lgkmcnt(0)
	v_mfma_f32_16x16x32_bf16 v[8:11], v[56:59], v[218:221], v[8:11]
	ds_read_b128 v[218:221], v169 offset:53248
	s_waitcnt lgkmcnt(0)
	v_mfma_f32_16x16x32_bf16 v[12:15], v[56:59], v[218:221], v[12:15]
	ds_read_b128 v[218:221], v170 offset:53312
	s_waitcnt lgkmcnt(0)
	v_mfma_f32_16x16x32_bf16 v[16:19], v[56:59], v[218:221], v[16:19]
	ds_read_b128 v[218:221], v171 offset:53312
	s_waitcnt lgkmcnt(0)
	v_mfma_f32_16x16x32_bf16 v[20:23], v[56:59], v[218:221], v[20:23]
	ds_read_b128 v[218:221], v172 offset:53248
	s_waitcnt lgkmcnt(0)
	v_mfma_f32_16x16x32_bf16 v[218:221], v[56:59], v[218:221], v[24:27]
	s_nop 2
	ds_read_b128 v[24:27], v173 offset:53248
	s_waitcnt lgkmcnt(0)
	v_mfma_f32_16x16x32_bf16 v[222:225], v[56:59], v[24:27], v[28:31]
	ds_read_b128 v[24:27], v174 offset:53312
	s_waitcnt lgkmcnt(0)
	v_mfma_f32_16x16x32_bf16 v[226:229], v[56:59], v[24:27], v[32:35]
	ds_read_b128 v[24:27], v175 offset:53312
	s_waitcnt lgkmcnt(0)
	v_mfma_f32_16x16x32_bf16 v[36:39], v[56:59], v[24:27], v[36:39]
	ds_read_b128 v[230:233], v84 offset:34880
	ds_read_b128 v[24:27], v168 offset:53312
	s_waitcnt lgkmcnt(0)
	v_mfma_f32_16x16x32_bf16 v[8:11], v[230:233], v[24:27], v[8:11]
	ds_read_b128 v[24:27], v169 offset:53312
	s_waitcnt lgkmcnt(0)
	v_mfma_f32_16x16x32_bf16 v[12:15], v[230:233], v[24:27], v[12:15]
	ds_read_b128 v[24:27], v170 offset:53248
	s_waitcnt lgkmcnt(0)
	v_mfma_f32_16x16x32_bf16 v[16:19], v[230:233], v[24:27], v[16:19]
	ds_read_b128 v[24:27], v171 offset:53248
	s_waitcnt lgkmcnt(0)
	v_mfma_f32_16x16x32_bf16 v[24:27], v[230:233], v[24:27], v[20:23]
	s_nop 2
	ds_read_b128 v[20:23], v172 offset:53312
	s_waitcnt lgkmcnt(0)
	v_mfma_f32_16x16x32_bf16 v[28:31], v[230:233], v[20:23], v[218:221]
	ds_read_b128 v[20:23], v173 offset:53312
	s_waitcnt lgkmcnt(0)
	v_mfma_f32_16x16x32_bf16 v[32:35], v[230:233], v[20:23], v[222:225]
	ds_read_b128 v[20:23], v174 offset:53248
	s_waitcnt lgkmcnt(0)
	v_mfma_f32_16x16x32_bf16 v[56:59], v[230:233], v[20:23], v[226:229]
	ds_read_b128 v[20:23], v175 offset:53248
	s_waitcnt lgkmcnt(0)
	v_mfma_f32_16x16x32_bf16 v[20:23], v[230:233], v[20:23], v[36:39]
	s_nop 2
	v_add_u32_e32 v36, s88, v96
	ds_read_b128 v[36:39], v36
	s_waitcnt lgkmcnt(0)
	s_barrier
	s_and_saveexec_b64 s[28:29], vcc
	s_cbranch_execnz .LBB0_828
	s_or_b64 exec, exec, s[28:29]
	v_cmp_gt_u32_e32 vcc, s86, v201
	s_and_saveexec_b64 s[28:29], vcc
	s_cbranch_execnz .LBB0_829
